# stack2 + CONV_KT 20: idle CUs of the in-projection GEMM's last round convert 20 instead of 12 deferred weight blocks per wave
# speedup vs baseline: 1.0093x; 1.0071x over previous
.LBB8_256:
	s_cmp_lt_i32 s92, 3
	s_mul_i32 s59, s59, s68
	s_cselect_b64 s[6:7], -1, 0
	s_sub_i32 s8, s58, s59
	s_sub_i32 s9, s8, s68
	s_cmp_ge_u32 s8, s68
	s_cselect_b32 s8, s9, s8
	s_sub_i32 s9, s8, s68
	s_cmp_ge_u32 s8, s68
	s_cselect_b32 s8, s9, s8
	s_xor_b32 s38, s8, s56
	s_sub_i32 s39, s38, s56
	s_mul_i32 s8, s39, 0xa0
	s_and_b32 s8, s8, 0xffffff00
	s_cmpk_lt_i32 s39, 0x9a
	v_readlane_b32 s10, v254, 2
	s_cselect_b32 s67, s8, 0x6000
	v_readlane_b32 s11, v254, 3
	s_add_u32 s68, s10, 0x200000
	s_addc_u32 s69, s11, 0
	s_add_u32 s54, s10, 0x800000
	s_addc_u32 s55, s11, 0
	s_add_u32 s36, s10, 0xc800000
	s_addc_u32 s37, s11, 0
	s_add_u32 s90, s10, 0x2a000000
	s_addc_u32 s91, s11, 0
	s_add_u32 s8, s10, 0x2b000000
	s_addc_u32 s9, s11, 0
	v_writelane_b32 v254, s8, 41
	s_nop 1
	v_writelane_b32 v254, s9, 42
	s_add_u32 s8, s10, 0x2c000000
	s_addc_u32 s9, s11, 0
	v_writelane_b32 v254, s8, 43
	s_nop 1
	v_writelane_b32 v254, s9, 44
	s_add_u32 s8, s10, 0x2e000000
	s_addc_u32 s9, s11, 0
	v_writelane_b32 v254, s8, 45
	s_add_u32 s88, s10, 0x36000000
	s_addc_u32 s89, s11, 0
	v_writelane_b32 v254, s9, 46
	s_and_b64 s[34:35], s[6:7], s[0:1]
	s_mov_b64 s[0:1], s[92:93]
	v_writelane_b32 v254, s0, 47
	s_andn2_b64 vcc, exec, s[34:35]
	s_nop 0
	v_writelane_b32 v254, s1, 48
	v_writelane_b32 v254, s2, 49
	v_writelane_b32 v254, s3, 50
	v_writelane_b32 v254, s68, 51
	s_nop 1
	v_writelane_b32 v254, s69, 52
	s_cbranch_vccnz .LBB8_357
	v_readlane_b32 s0, v254, 40
	s_waitcnt vmcnt(13) lgkmcnt(2)
	v_mbcnt_lo_u32_b32 v10, -1, 0
	v_mbcnt_hi_u32_b32 v10, -1, v10
	s_cmpk_gt_i32 s2, 0x99f
	s_waitcnt lgkmcnt(0)
	v_add_u32_e32 v0, s0, v10
	s_nop 0
	v_readfirstlane_b32 s1, v0
	s_cbranch_scc1 .LBB8_279
	v_lshlrev_b32_e32 v1, 4, v0
	v_add_u32_e32 v2, 0x2000, v1
	v_ashrrev_i32_e32 v3, 31, v2
	v_lshrrev_b32_e32 v3, 22, v3
	v_add_u32_e32 v3, v2, v3
	v_ashrrev_i32_e32 v8, 10, v3
	v_mul_i32_i24_e32 v3, 0x400, v8
	v_sub_u32_e32 v2, v2, v3
	v_lshrrev_b32_e32 v3, 4, v2
	v_bitop3_b32 v2, v3, v2, 32 bitop3:0x6c
	v_ashrrev_i32_e32 v3, 31, v2
	v_lshrrev_b32_e32 v3, 26, v3
	v_add_u32_e32 v3, v2, v3
	v_lshlrev_b32_e32 v4, 3, v8
	v_ashrrev_i32_e32 v9, 6, v3
	v_and_b32_e32 v4, -16, v4
	v_add_u32_e32 v4, v9, v4
	v_and_b32_e32 v5, 3, v9
	s_mov_b32 s0, 0x7ffe0
	v_lshrrev_b32_e32 v6, 2, v4
	v_lshlrev_b32_e32 v7, 1, v4
	v_and_b32_e32 v3, 0xc0, v3
	v_and_or_b32 v5, v4, s0, v5
	v_and_b32_e32 v6, 4, v6
	v_and_b32_e32 v7, 24, v7
	v_sub_u32_e32 v2, v2, v3
	v_mov_b32_e32 v3, 1
	v_or3_b32 v5, v5, v6, v7
	v_lshlrev_b32_e32 v6, 5, v8
	v_ashrrev_i16_sdwa v2, v3, sext(v2) dst_sel:DWORD dst_unused:UNUSED_PAD src0_sel:DWORD src1_sel:BYTE_0
	v_and_b32_e32 v6, 32, v6
	v_bfe_i32 v11, v2, 0, 16
	v_add_lshl_u32 v2, v6, v11, 1
	v_lshl_add_u32 v128, v5, 13, v2
	v_lshl_add_u32 v130, v4, 13, v2
	v_bfe_i32 v2, v0, 27, 1
	v_lshrrev_b32_e32 v2, 22, v2
	v_add_u32_e32 v2, v1, v2
	v_and_b32_e32 v2, 0xfffffc00, v2
	v_sub_u32_e32 v1, v1, v2
	v_lshrrev_b32_e32 v2, 4, v1
	v_ashrrev_i32_e32 v4, 31, v0
	v_bitop3_b32 v1, v2, v1, 32 bitop3:0x6c
	v_lshrrev_b32_e32 v4, 26, v4
	v_ashrrev_i32_e32 v2, 31, v1
	v_add_u32_e32 v0, v0, v4
	v_lshrrev_b32_e32 v2, 26, v2
	s_waitcnt vmcnt(12)
	v_ashrrev_i32_e32 v13, 6, v0
	v_add_u32_e32 v2, v1, v2
	v_lshlrev_b32_e32 v0, 3, v13
	v_ashrrev_i32_e32 v12, 6, v2
	v_and_b32_e32 v0, -16, v0
	v_add_u32_e32 v0, v12, v0
	v_and_b32_e32 v4, 3, v12
	s_ashr_i32 s58, s2, 31
	v_and_or_b32 v4, v0, s0, v4
	s_lshr_b32 s0, s58, 29
	s_add_i32 s0, s2, s0
	s_ashr_i32 s8, s1, 6
	s_ashr_i32 s6, s0, 3
	s_and_b32 s0, s0, -8
	s_ashr_i32 s10, s1, 8
	s_lshl_b32 s57, s8, 10
	s_sub_i32 s0, s2, s0
	s_cmp_lt_i32 s0, 0
	s_movk_i32 s59, 0x135
	s_cselect_b32 s7, s59, 0x134
	s_mul_i32 s0, s0, s7
	s_add_i32 s0, s0, s6
	s_mul_hi_i32 s6, s0, 0x3531dec1
	s_lshr_b32 s7, s6, 31
	s_ashr_i32 s6, s6, 7
	s_add_i32 s6, s6, s7
	s_lshl_b32 s7, s6, 3
	s_mulk_i32 s6, 0x268
	s_sub_i32 s6, s0, s6
	s_sext_i32_i16 s0, s6
	s_bfe_u32 s0, s0, 0x3001c
	s_add_i32 s9, s6, s0
	s_sext_i32_i16 s0, s9
	s_and_b32 s9, s9, 0xfff8
	s_sub_i32 s6, s6, s9
	s_sext_i32_i16 s6, s6
	v_lshrrev_b32_e32 v5, 2, v0
	v_lshlrev_b32_e32 v6, 1, v0
	v_and_b32_e32 v2, 0xc0, v2
	s_lshr_b32 s0, s0, 3
	s_add_i32 s68, s7, s6
	v_and_b32_e32 v5, 4, v5
	v_and_b32_e32 v6, 24, v6
	v_sub_u32_e32 v1, v1, v2
	s_ashr_i32 s69, s68, 31
	s_bfe_i64 s[12:13], s[0:1], 0x100000
	v_or3_b32 v4, v4, v5, v6
	v_lshlrev_b32_e32 v5, 5, v13
	v_ashrrev_i16_sdwa v1, v3, sext(v1) dst_sel:DWORD dst_unused:UNUSED_PAD src0_sel:DWORD src1_sel:BYTE_0
	s_lshl_b64 s[6:7], s[68:69], 21
	s_lshl_b64 s[12:13], s[12:13], 21
	v_and_b32_e32 v5, 32, v5
	v_bfe_i32 v14, v1, 0, 16
	s_add_u32 s28, s4, s12
	v_add_lshl_u32 v1, v5, v14, 1
	s_addc_u32 s29, s5, s13
	s_add_i32 s69, s57, 0
	v_lshl_add_u32 v132, v4, 13, v1
	s_add_i32 m0, s69, 0x10000
	v_lshl_add_u32 v134, v0, 13, v1
	global_load_lds_dwordx4 v132, s[28:29]
	s_add_i32 m0, s69, 0x12000
	s_add_u32 s12, s28, 0x100000
	global_load_lds_dwordx4 v128, s[28:29]
	s_addc_u32 s13, s29, 0
	s_add_i32 m0, s69, 0x14000
	v_mov_b32_e32 v133, 0
	global_load_lds_dwordx4 v132, s[12:13]
	s_add_i32 m0, s69, 0x16000
	s_add_u32 s70, s54, s6
	s_addc_u32 s71, s55, s7
	s_add_i32 s74, s69, 0x2000
	global_load_lds_dwordx4 v128, s[12:13]
	s_mov_b32 m0, s69
	s_add_u32 s6, s70, 0x100000
	global_load_lds_dwordx4 v134, s[70:71]
	s_mov_b32 m0, s74
	s_addc_u32 s7, s71, 0
	s_add_i32 s75, s69, 0x4000
	global_load_lds_dwordx4 v130, s[70:71]
	s_mov_b32 m0, s75
	s_add_i32 s76, s69, 0x6000
	global_load_lds_dwordx4 v134, s[6:7]
	s_mov_b32 m0, s76
	v_mov_b32_e32 v129, v133
	global_load_lds_dwordx4 v130, s[6:7]
	v_mov_b32_e32 v135, v133
	v_mov_b32_e32 v131, v133
	s_cmp_eq_u32 s10, 1
	s_mov_b32 s77, 0
	v_lshl_add_u64 v[6:7], s[28:29], 0, v[132:133]
	v_lshl_add_u64 v[4:5], s[28:29], 0, v[128:129]
	v_lshl_add_u64 v[0:1], s[70:71], 0, v[134:135]
	s_cselect_b64 s[6:7], -1, 0
	s_cmp_lg_u32 s10, 1
	v_lshl_add_u64 v[2:3], s[70:71], 0, v[130:131]
	s_cbranch_scc1 .LBB8_260
	s_barrier
